# attention QK block: n1 chain then n0 chain so n0 exps read accumulators directly (8 of 16 score copies removed)
# speedup vs baseline: 1.0222x; 1.0038x over previous
; __device__ __forceinline__ void attn_unit(const Params& P, unsigned char* lds, int h, int qb) {
;     ...
;         } else if (act) {
;             ATT_GAP(0, 32);
;         }
;         if (act) {
;             lsum += ps0 + ps1;
.LBB0_879:
	s_mov_b64 s[10:11], 0
	s_and_b64 vcc, exec, s[8:9]
	s_mov_b64 s[12:13], 0
	s_cbranch_vccz .LBB0_881
	v_mov_b64_e32 v[128:129], v[16:17]
	v_mov_b64_e32 v[130:131], v[18:19]
	v_mov_b64_e32 v[132:133], v[20:21]
	v_mov_b64_e32 v[134:135], v[22:23]
	v_mov_b64_e32 v[136:137], v[24:25]
	v_mov_b64_e32 v[138:139], v[26:27]
	v_mov_b64_e32 v[140:141], v[28:29]
	v_mov_b64_e32 v[142:143], v[30:31]
	v_mov_b32_e32 v2, v128
	v_mov_b32_e32 v4, v117
	v_exp_f32_e32 v11, v2
	v_mov_b32_e32 v2, v129
	s_mov_b64 s[12:13], -1
	v_exp_f32_e32 v223, v2
	v_mov_b32_e32 v2, v130
	v_exp_f32_e32 v219, v2
	v_mov_b32_e32 v2, v131
	v_exp_f32_e32 v225, v2
	v_mov_b32_e32 v2, v132
	v_exp_f32_e32 v13, v2
	v_mov_b32_e32 v2, v133
	v_exp_f32_e32 v15, v2
	v_mov_b32_e32 v2, v134
	v_exp_f32_e32 v181, v2
	v_mov_b32_e32 v2, v135
	v_exp_f32_e32 v183, v2
	v_mov_b32_e32 v2, v136
	v_exp_f32_e32 v209, v2
	v_mov_b32_e32 v2, v137
	v_cvt_pk_bf16_f32 v5, v181, v183
	v_exp_f32_e32 v211, v2
	v_mov_b32_e32 v2, v138
	v_exp_f32_e32 v213, v2
	v_mov_b32_e32 v2, v139
	v_cvt_pk_bf16_f32 v6, v209, v211
	v_exp_f32_e32 v215, v2
	v_mov_b32_e32 v2, v140
	v_exp_f32_e32 v217, v2
	v_mov_b32_e32 v2, v141
	v_cvt_pk_bf16_f32 v7, v213, v215
	v_exp_f32_e32 v221, v2
	v_mov_b32_e32 v2, v142
	v_exp_f32_e32 v227, v2
	v_mov_b32_e32 v2, v143
	v_cvt_pk_bf16_f32 v8, v217, v221
	v_exp_f32_e32 v229, v2
	v_mov_b32_e32 v2, v112
	v_exp_f32_e32 v10, v2
	v_mov_b32_e32 v2, v113
	v_cvt_pk_bf16_f32 v9, v227, v229
	v_exp_f32_e32 v222, v2
	v_mov_b32_e32 v2, v114
	v_exp_f32_e32 v218, v2
	v_mov_b32_e32 v2, v115
	v_exp_f32_e32 v224, v2
	v_mov_b32_e32 v2, v116
	v_exp_f32_e32 v12, v2
	v_pk_add_f32 v[2:3], v[10:11], 0 op_sel_hi:[1,0]
	v_exp_f32_e32 v14, v4
	v_mov_b32_e32 v4, v118
	v_pk_add_f32 v[2:3], v[2:3], v[222:223]
	v_exp_f32_e32 v180, v4
	v_mov_b32_e32 v4, v119
	v_pk_add_f32 v[2:3], v[2:3], v[218:219]
	v_exp_f32_e32 v182, v4
	v_mov_b32_e32 v4, v120
	v_pk_add_f32 v[2:3], v[2:3], v[224:225]
	v_exp_f32_e32 v208, v4
	v_mov_b32_e32 v4, v121
	v_pk_add_f32 v[2:3], v[2:3], v[12:13]
	v_exp_f32_e32 v210, v4
	v_mov_b32_e32 v4, v122
	v_pk_add_f32 v[2:3], v[2:3], v[14:15]
	v_exp_f32_e32 v212, v4
	v_mov_b32_e32 v4, v123
	v_pk_add_f32 v[2:3], v[2:3], v[180:181]
	v_exp_f32_e32 v214, v4
	v_mov_b32_e32 v4, v124
	v_pk_add_f32 v[2:3], v[2:3], v[182:183]
	v_cvt_pk_bf16_f32 v10, v10, v222
	v_pk_add_f32 v[2:3], v[2:3], v[208:209]
	v_exp_f32_e32 v216, v4
	v_mov_b32_e32 v4, v125
	v_pk_add_f32 v[2:3], v[2:3], v[210:211]
	v_cvt_pk_bf16_f32 v12, v12, v14
	v_pk_add_f32 v[2:3], v[2:3], v[212:213]
	v_exp_f32_e32 v220, v4
	v_mov_b32_e32 v4, v126
	v_pk_add_f32 v[2:3], v[2:3], v[214:215]
	v_cvt_pk_bf16_f32 v181, v212, v214
	v_pk_add_f32 v[2:3], v[2:3], v[216:217]
	v_exp_f32_e32 v226, v4
	v_pk_add_f32 v[2:3], v[2:3], v[220:221]
	v_mov_b32_e32 v4, v127
	v_pk_add_f32 v[2:3], v[2:3], v[226:227]
	v_exp_f32_e32 v228, v4
	v_cvt_pk_bf16_f32 v4, v13, v15
	v_pk_add_f32 v[230:231], v[2:3], v[228:229]
	v_cvt_pk_bf16_f32 v2, v11, v223
	v_cvt_pk_bf16_f32 v3, v219, v225
	v_cvt_pk_bf16_f32 v11, v218, v224
	v_cvt_pk_bf16_f32 v13, v180, v182
	v_cvt_pk_bf16_f32 v180, v208, v210
	v_cvt_pk_bf16_f32 v182, v216, v220
	v_cvt_pk_bf16_f32 v183, v226, v228
	s_add_i32 s25, s21, 1
	s_and_b64 vcc, exec, s[10:11]
	s_cbranch_vccz .LBB0_893
	s_branch .LBB0_882

; #define SBAR() __builtin_amdgcn_sched_barrier(0)
; __device__ __forceinline__ void attn_unit(const Params& P, unsigned char* lds, int h, int qb) {
;     ...
;         if (act && actn) {
;             const unsigned char* Kn = lds + ((t + 1) & 1) * KBUF + r32 * KROW + hi * 16;
;             SBAR();
; #pragma unroll
;             for (int g = 0; g < 6; ++g) {
;                 const bf16x8 ka = *(const bf16x8*)(Kn + g * 32), kb = *(const bf16x8*)(Kn + 32 * KROW + g * 32);
;                 n0 = __builtin_amdgcn_mfma_f32_32x32x16_bf16(ka, qr[g], g == 0 ? negm : n0, 0, 0, 0);
;                 SBAR();
;                 ATT_GAP((32 * (2 * g)) / 12, (32 * (2 * g + 1)) / 12);
;                 SBAR();
;                 n1 = __builtin_amdgcn_mfma_f32_32x32x16_bf16(kb, qr[g], g == 0 ? negm : n1, 0, 0, 0);
;                 SBAR();
;                 ATT_GAP((32 * (2 * g + 1)) / 12, (32 * (2 * g + 2)) / 12);
;                 SBAR();
;             }
;             if ((t + 1) * 64 + 63 > qw0) attn_mask(n0, n1, (t + 1) * 64, qg, hi);
.LBB0_882:
	s_waitcnt lgkmcnt(3)
	v_mfma_f32_32x32x16_bf16 v[80:95], v[210:213], v[160:163], v[64:79]
	v_exp_f32_e32 v15, v16
	v_exp_f32_e32 v97, v17
	v_exp_f32_e32 v99, v18
	v_cvt_pk_bf16_f32 v2, v15, v97
	ds_read_b128 v[210:213], v208 offset:6784
	s_waitcnt lgkmcnt(3)
	v_mfma_f32_32x32x16_bf16 v[80:95], v[214:217], v[144:147], v[80:95]
	v_exp_f32_e32 v101, v19
	v_exp_f32_e32 v103, v20
	v_cvt_pk_bf16_f32 v3, v99, v101
	v_exp_f32_e32 v105, v21
	ds_read_b128 v[214:217], v208 offset:6816
	s_waitcnt lgkmcnt(3)
	v_mfma_f32_32x32x16_bf16 v[80:95], v[218:221], v[148:151], v[80:95]
	v_exp_f32_e32 v107, v22
	v_cvt_pk_bf16_f32 v4, v103, v105
	v_exp_f32_e32 v109, v23
	v_exp_f32_e32 v111, v24
	ds_read_b128 v[218:221], v208
	s_waitcnt lgkmcnt(3)
	v_mfma_f32_32x32x16_bf16 v[80:95], v[222:225], v[152:155], v[80:95]
	v_cvt_pk_bf16_f32 v5, v107, v109
	v_exp_f32_e32 v129, v25
	v_exp_f32_e32 v131, v26
	v_cvt_pk_bf16_f32 v6, v111, v129
	ds_read_b128 v[222:225], v208 offset:32
	s_waitcnt lgkmcnt(3)
	v_mfma_f32_32x32x16_bf16 v[80:95], v[210:213], v[156:159], v[80:95]
	v_exp_f32_e32 v133, v27
	v_exp_f32_e32 v135, v28
	v_cvt_pk_bf16_f32 v7, v131, v133
	v_exp_f32_e32 v137, v29
	ds_read_b128 v[210:213], v208 offset:64
	s_waitcnt lgkmcnt(3)
	v_mfma_f32_32x32x16_bf16 v[80:95], v[214:217], v[164:167], v[80:95]
	v_exp_f32_e32 v139, v30
	v_cvt_pk_bf16_f32 v8, v135, v137
	v_exp_f32_e32 v141, v31
	v_exp_f32_e32 v14, v112
	ds_read_b128 v[214:217], v208 offset:96
	s_waitcnt lgkmcnt(3)
	v_mfma_f32_32x32x16_bf16 v[16:31], v[218:221], v[160:163], v[64:79]
	v_cvt_pk_bf16_f32 v9, v139, v141
	v_exp_f32_e32 v96, v113
	v_exp_f32_e32 v98, v114
	v_cvt_pk_bf16_f32 v10, v14, v96
	ds_read_b128 v[218:221], v208 offset:128
	s_waitcnt lgkmcnt(3)
	v_mfma_f32_32x32x16_bf16 v[16:31], v[222:225], v[144:147], v[16:31]
	v_exp_f32_e32 v100, v115
	v_exp_f32_e32 v102, v116
	v_cvt_pk_bf16_f32 v11, v98, v100
	v_exp_f32_e32 v104, v117
	ds_read_b128 v[222:225], v208 offset:160
	s_waitcnt lgkmcnt(3)
	v_mfma_f32_32x32x16_bf16 v[16:31], v[210:213], v[148:151], v[16:31]
	v_exp_f32_e32 v106, v118
	v_cvt_pk_bf16_f32 v12, v102, v104
	v_exp_f32_e32 v108, v119
	v_exp_f32_e32 v110, v120
	s_waitcnt lgkmcnt(2)
	v_mfma_f32_32x32x16_bf16 v[16:31], v[214:217], v[152:155], v[16:31]
	v_cvt_pk_bf16_f32 v13, v106, v108
	v_exp_f32_e32 v128, v121
	v_exp_f32_e32 v130, v122
	v_cvt_pk_bf16_f32 v180, v110, v128
	s_waitcnt lgkmcnt(1)
	v_mfma_f32_32x32x16_bf16 v[16:31], v[218:221], v[156:159], v[16:31]
	v_exp_f32_e32 v132, v123
	v_exp_f32_e32 v134, v124
	v_cvt_pk_bf16_f32 v181, v130, v132
	v_exp_f32_e32 v136, v125
	s_waitcnt lgkmcnt(0)
	v_mfma_f32_32x32x16_bf16 v[16:31], v[222:225], v[164:167], v[16:31]
	v_exp_f32_e32 v138, v126
	v_cvt_pk_bf16_f32 v182, v134, v136
	v_exp_f32_e32 v140, v127
	s_cmp_le_i32 s20, s15
	v_cvt_pk_bf16_f32 v183, v138, v140
	s_cbranch_scc1 .LBB0_884
	s_nop 3
	v_add_u32_e32 v112, s20, v249
	v_subrev_u32_e32 v114, 31, v112
	v_subrev_u32_e32 v113, 63, v112
	v_cmp_le_i32_e32 vcc, v114, v198
	s_nop 1
	v_cndmask_b32_e32 v80, v244, v80, vcc
	v_cmp_lt_i32_e32 vcc, v113, v198
	s_nop 1
	v_cndmask_b32_e32 v17, v244, v17, vcc
	v_cmp_le_i32_e32 vcc, v113, v198
	v_subrev_u32_e32 v113, 30, v112
	s_nop 0
	v_cndmask_b32_e32 v16, v244, v16, vcc
	v_cmp_le_i32_e32 vcc, v113, v198
	v_subrev_u32_e32 v113, 61, v112
	s_nop 0
	v_cndmask_b32_e32 v81, v244, v81, vcc
	v_cmp_le_i32_e32 vcc, v113, v198
	v_subrev_u32_e32 v113, 29, v112
	s_nop 0
	v_cndmask_b32_e32 v18, v244, v18, vcc
	v_cmp_le_i32_e32 vcc, v113, v198
	v_subrev_u32_e32 v113, 60, v112
	s_nop 0
	v_cndmask_b32_e32 v82, v244, v82, vcc
	v_cmp_le_i32_e32 vcc, v113, v198
	v_subrev_u32_e32 v113, 28, v112
	s_nop 0
	v_cndmask_b32_e32 v19, v244, v19, vcc
	v_cmp_le_i32_e32 vcc, v113, v198
	v_subrev_u32_e32 v113, 55, v112
	s_nop 0
	v_cndmask_b32_e32 v83, v244, v83, vcc
	v_cmp_le_i32_e32 vcc, v113, v198
	v_subrev_u32_e32 v113, 23, v112
	s_nop 0
	v_cndmask_b32_e32 v20, v244, v20, vcc
	v_cmp_le_i32_e32 vcc, v113, v198
	v_subrev_u32_e32 v113, 54, v112
	s_nop 0
	v_cndmask_b32_e32 v84, v244, v84, vcc
	v_cmp_le_i32_e32 vcc, v113, v198
	v_subrev_u32_e32 v113, 22, v112
	s_nop 0
	v_cndmask_b32_e32 v21, v244, v21, vcc
	v_cmp_le_i32_e32 vcc, v113, v198
	v_subrev_u32_e32 v113, 53, v112
	s_nop 0
	v_cndmask_b32_e32 v85, v244, v85, vcc
	v_cmp_le_i32_e32 vcc, v113, v198
	v_subrev_u32_e32 v113, 21, v112
	s_nop 0
	v_cndmask_b32_e32 v22, v244, v22, vcc
	v_cmp_le_i32_e32 vcc, v113, v198
	v_subrev_u32_e32 v113, 52, v112
	s_nop 0
	v_cndmask_b32_e32 v86, v244, v86, vcc
	v_cmp_le_i32_e32 vcc, v113, v198
	v_subrev_u32_e32 v113, 20, v112
	s_nop 0
	v_cndmask_b32_e32 v23, v244, v23, vcc
	v_cmp_le_i32_e32 vcc, v113, v198
	v_subrev_u32_e32 v113, 47, v112
	s_nop 0
	v_cndmask_b32_e32 v87, v244, v87, vcc
	v_cmp_le_i32_e32 vcc, v113, v198
	v_add_u32_e32 v113, -15, v112
	s_nop 0
	v_cndmask_b32_e32 v24, v244, v24, vcc
	v_cmp_le_i32_e32 vcc, v113, v198
	v_subrev_u32_e32 v113, 46, v112
	s_nop 0
	v_cndmask_b32_e32 v88, v244, v88, vcc
	v_cmp_le_i32_e32 vcc, v113, v198
	v_add_u32_e32 v113, -14, v112
	s_nop 0
	v_cndmask_b32_e32 v25, v244, v25, vcc
	v_cmp_le_i32_e32 vcc, v113, v198
	v_subrev_u32_e32 v113, 45, v112
	s_nop 0
	v_cndmask_b32_e32 v89, v244, v89, vcc
	v_cmp_le_i32_e32 vcc, v113, v198
	v_add_u32_e32 v113, -13, v112
	s_nop 0
	v_cndmask_b32_e32 v26, v244, v26, vcc
	v_cmp_le_i32_e32 vcc, v113, v198
	v_subrev_u32_e32 v113, 44, v112
	s_nop 0
	v_cndmask_b32_e32 v90, v244, v90, vcc
	v_cmp_le_i32_e32 vcc, v113, v198
	v_add_u32_e32 v113, -12, v112
	s_nop 0
	v_cndmask_b32_e32 v27, v244, v27, vcc
	v_cmp_le_i32_e32 vcc, v113, v198
	v_subrev_u32_e32 v113, 39, v112
	s_nop 0
	v_cndmask_b32_e32 v91, v244, v91, vcc
	v_cmp_le_i32_e32 vcc, v113, v198
	v_add_u32_e32 v113, -7, v112
	s_nop 0
	v_cndmask_b32_e32 v28, v244, v28, vcc
	v_cmp_le_i32_e32 vcc, v113, v198
	v_subrev_u32_e32 v113, 38, v112
	s_nop 0
	v_cndmask_b32_e32 v92, v244, v92, vcc
	v_cmp_le_i32_e32 vcc, v113, v198
	v_add_u32_e32 v113, -6, v112
	s_nop 0
	v_cndmask_b32_e32 v29, v244, v29, vcc
	v_cmp_le_i32_e32 vcc, v113, v198
	v_subrev_u32_e32 v113, 37, v112
	s_nop 0
	v_cndmask_b32_e32 v93, v244, v93, vcc
	v_cmp_le_i32_e32 vcc, v113, v198
	v_add_u32_e32 v113, -5, v112
	s_nop 0
	v_cndmask_b32_e32 v30, v244, v30, vcc
	v_cmp_le_i32_e32 vcc, v113, v198
	v_subrev_u32_e32 v113, 36, v112
	v_add_u32_e32 v112, -4, v112
	v_cndmask_b32_e32 v94, v244, v94, vcc
	v_cmp_le_i32_e32 vcc, v113, v198
	s_nop 1
	v_cndmask_b32_e32 v31, v244, v31, vcc
	v_cmp_le_i32_e32 vcc, v112, v198
	s_nop 1
	v_cndmask_b32_e32 v95, v244, v95, vcc

; #define SBAR() __builtin_amdgcn_sched_barrier(0)
; __device__ __forceinline__ void attn_unit(const Params& P, unsigned char* lds, int h, int qb) {
;     ...
;         if (act && actn) {
;             const unsigned char* Kn = lds + ((t + 1) & 1) * KBUF + r32 * KROW + hi * 16;
;             SBAR();
; #pragma unroll
;             for (int g = 0; g < 6; ++g) {
;                 const bf16x8 ka = *(const bf16x8*)(Kn + g * 32), kb = *(const bf16x8*)(Kn + 32 * KROW + g * 32);
.Lattn_mx:
	s_cmp_ge_i32 s21, s18
	s_cbranch_scc1 .Lattn_nopf
	s_add_i32 s10, s21, 1
	s_bitcmp1_b32 s10, 0
	s_cselect_b32 s10, 0x3400, 0
	v_add_u32_e32 v208, s10, v248
	ds_read_b128 v[210:213], v208 offset:6656
	ds_read_b128 v[214:217], v208 offset:6688
	ds_read_b128 v[218:221], v208 offset:6720
	ds_read_b128 v[222:225], v208 offset:6752

; __device__ __forceinline__ void attn_unit(const Params& P, unsigned char* lds, int h, int qb) {
;     ...
;             if (t == 0 || __any(mx > THR)) {
;                 const float dl = (t == 0) ? mx : fmaxf(mx, 0.f), f = __builtin_amdgcn_exp2f(-dl);
;                 m += dl; lsum *= f;
; #pragma unroll
;                 for (int r = 0; r < 16; ++r) { c0[r] -= dl; c1[r] -= dl; o0[r] *= f; o1[r] *= f; negm[r] = -m; }
;             }
;         }
;     ...
;         c0 = n0; c1 = n1;
.LBB0_888:
	s_cbranch_execz .LBB0_891
	v_exp_f32_e64 v4, -v2
	v_add_f32_e32 v0, v0, v2
	v_xor_b32_e32 v96, 0x80000000, v0
	v_sub_f32_e32 v31, v31, v2
	v_sub_f32_e32 v30, v30, v2
	v_sub_f32_e32 v29, v29, v2
	v_sub_f32_e32 v28, v28, v2
	v_sub_f32_e32 v27, v27, v2
	v_sub_f32_e32 v26, v26, v2
	v_sub_f32_e32 v25, v25, v2
	v_sub_f32_e32 v24, v24, v2
	v_sub_f32_e32 v23, v23, v2
	v_sub_f32_e32 v22, v22, v2
	v_sub_f32_e32 v21, v21, v2
	v_sub_f32_e32 v20, v20, v2
	v_sub_f32_e32 v19, v19, v2
	v_sub_f32_e32 v18, v18, v2
	v_sub_f32_e32 v17, v17, v2
	v_sub_f32_e32 v16, v16, v2
	v_sub_f32_e32 v127, v95, v2
	v_sub_f32_e32 v126, v94, v2
	v_sub_f32_e32 v125, v93, v2
	v_sub_f32_e32 v124, v92, v2
	v_sub_f32_e32 v123, v91, v2
	v_sub_f32_e32 v122, v90, v2
	v_sub_f32_e32 v121, v89, v2
	v_sub_f32_e32 v120, v88, v2
	v_sub_f32_e32 v119, v87, v2
	v_sub_f32_e32 v118, v86, v2
	v_sub_f32_e32 v117, v85, v2
	v_sub_f32_e32 v116, v84, v2
	v_sub_f32_e32 v115, v83, v2
	v_sub_f32_e32 v114, v82, v2
	v_sub_f32_e32 v113, v81, v2
	v_sub_f32_e32 v112, v80, v2
	v_pk_mul_f32 v[62:63], v[62:63], v[4:5] op_sel_hi:[1,0]
	v_pk_mul_f32 v[60:61], v[60:61], v[4:5] op_sel_hi:[1,0]
	v_pk_mul_f32 v[58:59], v[58:59], v[4:5] op_sel_hi:[1,0]
	v_pk_mul_f32 v[56:57], v[56:57], v[4:5] op_sel_hi:[1,0]
	v_pk_mul_f32 v[54:55], v[54:55], v[4:5] op_sel_hi:[1,0]
	v_pk_mul_f32 v[52:53], v[52:53], v[4:5] op_sel_hi:[1,0]
	v_pk_mul_f32 v[50:51], v[50:51], v[4:5] op_sel_hi:[1,0]
	v_pk_mul_f32 v[48:49], v[48:49], v[4:5] op_sel_hi:[1,0]
	v_pk_mul_f32 v[46:47], v[46:47], v[4:5] op_sel_hi:[1,0]
	v_pk_mul_f32 v[44:45], v[44:45], v[4:5] op_sel_hi:[1,0]
	v_pk_mul_f32 v[42:43], v[42:43], v[4:5] op_sel_hi:[1,0]
	v_pk_mul_f32 v[40:41], v[40:41], v[4:5] op_sel_hi:[1,0]
	v_pk_mul_f32 v[38:39], v[38:39], v[4:5] op_sel_hi:[1,0]
	v_pk_mul_f32 v[36:37], v[36:37], v[4:5] op_sel_hi:[1,0]
	v_pk_mul_f32 v[34:35], v[34:35], v[4:5] op_sel_hi:[1,0]
	v_pk_mul_f32 v[32:33], v[32:33], v[4:5] op_sel_hi:[1,0]
	v_mul_f32_e32 v236, v236, v4
	v_mov_b32_e32 v97, v96
	v_mov_b32_e32 v98, v96
	v_mov_b32_e32 v99, v96
	v_mov_b32_e32 v100, v96
	v_mov_b32_e32 v101, v96
	v_mov_b32_e32 v102, v96
	v_mov_b32_e32 v103, v96
	v_mov_b32_e32 v104, v96
	v_mov_b32_e32 v105, v96
	v_mov_b32_e32 v106, v96
	v_mov_b32_e32 v107, v96
	v_mov_b32_e32 v108, v96
	v_mov_b32_e32 v109, v96
	v_mov_b32_e32 v110, v96
	v_mov_b32_e32 v111, v96
	v_mov_b32_e32 v79, v96
	v_mov_b32_e32 v78, v96
	v_mov_b32_e32 v77, v96
	v_mov_b32_e32 v76, v96
	v_mov_b32_e32 v75, v96
	v_mov_b32_e32 v74, v96
	v_mov_b32_e32 v73, v96
	v_mov_b32_e32 v72, v96
	v_mov_b32_e32 v71, v96
	v_mov_b32_e32 v70, v96
	v_mov_b32_e32 v69, v96
	v_mov_b32_e32 v68, v96
	v_mov_b32_e32 v67, v96
	v_mov_b32_e32 v66, v96
	v_mov_b32_e32 v65, v96
	v_mov_b32_e32 v64, v96
	s_cmp_ge_i32 s21, s18
	s_cbranch_scc1 .LBB0_879
	s_branch .LBB0_892
.LBB0_890:
.LBB0_891:
	v_mov_b64_e32 v[126:127], v[94:95]
	v_mov_b64_e32 v[124:125], v[92:93]
	v_mov_b64_e32 v[122:123], v[90:91]
	v_mov_b64_e32 v[120:121], v[88:89]
	v_mov_b64_e32 v[118:119], v[86:87]
	v_mov_b64_e32 v[116:117], v[84:85]
	v_mov_b64_e32 v[114:115], v[82:83]
	v_mov_b64_e32 v[112:113], v[80:81]
	s_cmp_ge_i32 s21, s18
	s_cbranch_scc1 .LBB0_879
